# P10: K/V tile LDS-DMA loads marked sc1
# baseline (speedup 1.0000x reference)
.LBB0_1285:
	s_and_b64 vcc, exec, s[6:7]
	s_cbranch_vccz .LBB0_1221
	s_and_b32 s6, s84, 0xffff
	s_mul_i32 s6, s6, 0xaaab
	s_lshr_b32 s7, s6, 21
	s_mul_i32 s7, s7, 48
	s_sub_i32 s7, s84, s7
	s_and_b32 s84, s7, 0xff
	s_mul_i32 s8, s84, 0xab
	s_lshr_b32 s6, s6, 13
	s_bfe_u32 s10, s8, 0x5000b
	s_and_b32 s53, s6, 0xff00
	s_mul_i32 s8, s10, 12
	s_lshl_b32 s14, s10, 12
	s_sub_i32 s88, 0xf00, s53
	s_sub_i32 s7, s7, s8
	s_or_b32 s50, s14, s88
	s_and_b32 s54, s7, 0xff
	s_mul_i32 s6, s50, 0x1200
	s_add_u32 s6, s3, s6
	s_addc_u32 s7, s56, 0
	s_mul_i32 s85, s54, 0x180
	s_add_u32 s8, s6, s85
	s_addc_u32 s9, s7, 0
	s_mul_i32 s86, s10, 0x1200000
	s_add_u32 s6, s57, s86
	s_addc_u32 s7, s58, 0
	s_add_u32 s6, s6, s85
	v_readfirstlane_b32 s52, v213
	s_addc_u32 s7, s7, 0
	s_lshr_b32 s82, s52, 6
	s_lshl_b32 s24, s82, 5
	v_or_b32_e32 v240, s24, v212
	v_mov_b64_e32 v[0:1], s[8:9]
	v_mad_u64_u32 v[0:1], s[8:9], v240, s80, v[0:1]
	v_mov_b32_e32 v153, v145
	v_lshl_add_u64 v[0:1], v[0:1], 0, v[152:153]
	global_load_dwordx4 v[96:99], v[0:1], off
	global_load_dwordx4 v[100:103], v[0:1], off offset:32
	global_load_dwordx4 v[104:107], v[0:1], off offset:64
	global_load_dwordx4 v[108:111], v[0:1], off offset:96
	global_load_dwordx4 v[112:115], v[0:1], off offset:128
	global_load_dwordx4 v[116:119], v[0:1], off offset:160
	global_load_dwordx4 v[120:123], v[0:1], off offset:192
	global_load_dwordx4 v[124:127], v[0:1], off offset:224
	global_load_dwordx4 v[128:131], v[0:1], off offset:256
	global_load_dwordx4 v[132:135], v[0:1], off offset:288
	global_load_dwordx4 v[136:139], v[0:1], off offset:320
	global_load_dwordx4 v[140:143], v[0:1], off offset:352
	s_lshl_b32 s51, s82, 10
	v_or_b32_e32 v0, s51, v147
	v_mul_hi_i32 v1, v0, s81
	v_lshrrev_b32_e32 v2, 31, v1
	v_ashrrev_i32_e32 v1, 7, v1
	v_add_u32_e32 v1, v1, v2
	v_mul_i32_i24_e32 v2, 0x190, v1
	v_sub_u32_e32 v2, v0, v2
	v_cmp_gt_i32_e32 vcc, s73, v2
	v_min_i32_e32 v1, 63, v1
	s_cmpk_lt_u32 s52, 0x640
	v_cndmask_b32_e32 v2, 0, v2, vcc
	s_cselect_b64 s[18:19], -1, 0
	s_cmpk_gt_u32 s52, 0x63f
	v_mad_u64_u32 v[160:161], s[8:9], v1, s80, v[2:3]
	s_cbranch_scc1 .LBB0_1288
	s_add_i32 m0, s51, 0
	s_nop 0
	global_load_lds_dwordx4 v160, s[6:7] sc1
.LBB0_1288:
	v_add_u32_e32 v1, 0x2000, v0
	v_mul_hi_i32 v2, v1, s81
	v_lshrrev_b32_e32 v3, 31, v2
	v_ashrrev_i32_e32 v2, 7, v2
	v_add_u32_e32 v2, v2, v3
	v_mul_i32_i24_e32 v3, 0x190, v2
	v_sub_u32_e32 v3, v1, v3
	v_cmp_gt_i32_e32 vcc, s73, v3
	s_add_i32 s55, s82, 8
	v_min_i32_e32 v4, 63, v2
	v_cndmask_b32_e32 v2, 0, v3, vcc
	s_cmpk_lt_u32 s52, 0x440
	s_cselect_b64 s[8:9], -1, 0
	s_cmpk_gt_u32 s52, 0x43f
	v_mad_u64_u32 v[162:163], s[10:11], v4, s80, v[2:3]
	s_cbranch_scc1 .LBB0_1290
	s_lshl_b32 s10, s55, 10
	s_add_i32 m0, s10, 0
	s_nop 0
	global_load_lds_dwordx4 v162, s[6:7] sc1
.LBB0_1290:
	v_add_u32_e32 v2, 0x4000, v0
	v_mul_hi_i32 v3, v2, s81
	v_lshrrev_b32_e32 v4, 31, v3
	v_ashrrev_i32_e32 v3, 7, v3
	v_add_u32_e32 v3, v3, v4
	v_mul_i32_i24_e32 v4, 0x190, v3
	v_sub_u32_e32 v4, v2, v4
	v_cmp_gt_i32_e32 vcc, s73, v4
	s_add_i32 s82, s82, 16
	v_min_i32_e32 v3, 63, v3
	v_cndmask_b32_e32 v4, 0, v4, vcc
	s_cmpk_lt_u32 s52, 0x240
	s_cselect_b64 s[10:11], -1, 0
	s_cmpk_gt_u32 s52, 0x23f
	v_mad_u64_u32 v[164:165], s[12:13], v3, s80, v[4:5]
	s_cbranch_scc1 .LBB0_1292
	s_lshl_b32 s12, s82, 10
	s_add_i32 m0, s12, 0
	s_nop 0
	global_load_lds_dwordx4 v164, s[6:7] sc1
.LBB0_1292:
	v_add_u32_e32 v3, 0x6000, v0
	v_mul_hi_i32 v4, v3, s81
	v_lshrrev_b32_e32 v5, 31, v4
	v_ashrrev_i32_e32 v4, 7, v4
	v_add_u32_e32 v4, v4, v5
	v_mul_i32_i24_e32 v5, 0x190, v4
	v_sub_u32_e32 v3, v3, v5
	v_cmp_gt_i32_e32 vcc, s73, v3
	v_min_i32_e32 v5, 63, v4
	s_cmp_lt_u32 s52, 64
	v_cndmask_b32_e32 v4, 0, v3, vcc
	s_cselect_b64 s[12:13], -1, 0
	s_cmp_gt_u32 s52, 63
	v_mad_u64_u32 v[166:167], s[16:17], v5, s80, v[4:5]
	s_cbranch_scc1 .LBB0_1294
	s_add_i32 m0, 0, 0x6000
	s_nop 0
	global_load_lds_dwordx4 v166, s[6:7] sc1
.LBB0_1294:
	s_lshl_b32 s87, s54, 22
	v_mul_hi_i32 v3, v0, s76
	s_add_u32 s15, s59, s87
	v_lshrrev_b32_e32 v4, 31, v3
	v_ashrrev_i32_e32 v3, 5, v3
	s_addc_u32 s16, s60, 0
	s_lshl_b32 s14, s14, 1
	v_add_u32_e32 v3, v3, v4
	s_add_u32 s20, s15, s14
	v_mul_lo_u32 v4, v3, s70
	s_addc_u32 s21, s16, 0
	v_sub_u32_e32 v0, v0, v4
	v_cmp_gt_i32_e32 vcc, s77, v0
	s_cmpk_lt_u32 s52, 0x480
	v_min_i32_e32 v3, 0x7f, v3
	v_cndmask_b32_e32 v0, 0, v0, vcc
	s_cselect_b64 s[14:15], -1, 0
	v_lshl_add_u32 v144, v3, 15, v0
	s_and_b64 vcc, exec, s[14:15]
	s_cbranch_vccz .LBB0_1296
	s_add_i32 s16, s51, 0
	s_add_i32 m0, s16, 0xc800
	s_nop 0
	global_load_lds_dwordx4 v144, s[20:21] sc1
.LBB0_1296:
	v_mul_hi_i32 v0, v1, s76
	v_lshrrev_b32_e32 v3, 31, v0
	v_ashrrev_i32_e32 v0, 5, v0
	v_add_u32_e32 v0, v0, v3
	v_mul_lo_u32 v3, v0, s70
	v_sub_u32_e32 v1, v1, v3
	v_cmp_gt_i32_e32 vcc, s77, v1
	v_min_i32_e32 v0, 0x7f, v0
	s_cmpk_lt_u32 s52, 0x280
	v_cndmask_b32_e32 v1, 0, v1, vcc
	s_cselect_b64 s[16:17], -1, 0
	s_cmpk_gt_u32 s52, 0x27f
	v_lshl_add_u32 v156, v0, 15, v1
	s_cbranch_scc1 .LBB0_1298
	s_lshl_b32 s33, s55, 10
	s_add_i32 s33, s33, 0
	s_add_i32 m0, s33, 0xc800
	s_nop 0
	global_load_lds_dwordx4 v156, s[20:21] sc1
.LBB0_1298:
	v_mul_hi_i32 v0, v2, s76
	v_lshrrev_b32_e32 v1, 31, v0
	v_ashrrev_i32_e32 v0, 5, v0
	v_add_u32_e32 v0, v0, v1
	v_mul_lo_u32 v1, v0, s70
	v_sub_u32_e32 v1, v2, v1
	v_cmp_gt_i32_e32 vcc, s77, v1
	v_min_i32_e32 v0, 0x7f, v0
	s_cmpk_lt_u32 s52, 0x80
	v_cndmask_b32_e32 v1, 0, v1, vcc
	s_cselect_b64 s[38:39], -1, 0
	s_cmpk_gt_u32 s52, 0x7f
	v_lshl_add_u32 v158, v0, 15, v1
	s_cbranch_scc1 .LBB0_1300
	s_lshl_b32 s33, s82, 10
	s_add_i32 s33, s33, 0
	s_add_i32 m0, s33, 0xc800
	s_nop 0
	global_load_lds_dwordx4 v158, s[20:21] sc1

.LBB0_1307:
	s_lshl_b32 s33, s82, 10
	v_mov_b32_e32 v159, v145
	s_add_i32 s33, s33, 0
	v_lshl_add_u64 v[0:1], s[20:21], 0, v[158:159]
	s_add_i32 m0, s33, 0x11000
	v_lshl_add_u64 v[0:1], v[0:1], 0, s[26:27]
	global_load_lds_dwordx4 v[0:1], off sc1

.LBB0_1313:
	s_and_b32 s89, s85, 1
	s_add_i32 s33, s52, 1
	s_cmp_lg_u32 s52, 2
	s_mov_b32 s86, s52
	s_cselect_b32 s52, s33, 0
	s_add_i32 s85, s85, 1
	s_cmp_ge_u32 s85, s53
	s_cselect_b32 s96, 0, 1
	s_cmp_eq_u64 s[10:11], 0
	s_cselect_b32 s97, s96, 0
	s_cmp_eq_u64 s[16:17], 0
	s_cselect_b32 s99, s96, 0
	s_xor_b32 s90, s89, 1
	s_mulk_i32 s90, 0x6400
	s_mul_i32 s91, s52, 0x4800
	s_add_i32 s91, s91, 0xc800
	s_mulk_i32 s89, 0x6400
	s_sub_i32 s33, s84, 63
	s_waitcnt vmcnt(0)
	s_barrier
	s_cmp_gt_u32 s33, s54
	s_cbranch_scc1 .Lfa_noqk
	v_add3_u32 v144, v215, s89, v201
	ds_read_b128 v[168:171], v144
	ds_read_b128 v[172:175], v144 offset:32
	ds_read_b128 v[176:179], v144 offset:64
	ds_read_b128 v[180:183], v144 offset:96
	v_xor_b32_e32 v64, 0x80000000, v242
	v_mov_b32_e32 v65, v64
	v_mov_b32_e32 v66, v64
	v_mov_b32_e32 v67, v64
	v_mov_b32_e32 v68, v64
	v_mov_b32_e32 v69, v64
	v_mov_b32_e32 v70, v64
	v_mov_b32_e32 v71, v64
	v_mov_b32_e32 v72, v64
	v_mov_b32_e32 v73, v64
	v_mov_b32_e32 v74, v64
	v_mov_b32_e32 v75, v64
	v_mov_b32_e32 v76, v64
	v_mov_b32_e32 v77, v64
	v_mov_b32_e32 v78, v64
	v_mov_b32_e32 v79, v64
	s_nop 1
	s_waitcnt lgkmcnt(3)
	v_mfma_f32_32x32x16_bf16 v[80:95], v[168:171], v[96:99], v[64:79]
	ds_read_b128 v[168:171], v144 offset:128
	s_waitcnt lgkmcnt(3)
	v_mfma_f32_32x32x16_bf16 v[80:95], v[172:175], v[100:103], v[80:95]
	ds_read_b128 v[172:175], v144 offset:160
	s_cmp_lg_u32 s96, 0
	s_cbranch_scc0 .Lfa_ls1
	s_add_i32 m0, s90, s51
	s_nop 0
	global_load_lds_dwordx4 v160, s[92:93] sc1
.Lfa_ls1:
	s_waitcnt lgkmcnt(3)
	v_mfma_f32_32x32x16_bf16 v[80:95], v[176:179], v[104:107], v[80:95]
	ds_read_b128 v[176:179], v144 offset:192
	s_waitcnt lgkmcnt(3)
	v_mfma_f32_32x32x16_bf16 v[80:95], v[180:183], v[108:111], v[80:95]
	ds_read_b128 v[180:183], v144 offset:224
	s_waitcnt lgkmcnt(3)
	v_mfma_f32_32x32x16_bf16 v[80:95], v[168:171], v[112:115], v[80:95]
	ds_read_b128 v[168:171], v144 offset:256
	s_cmp_lg_u32 s96, 0
	s_cbranch_scc0 .Lfa_ls2
	s_add_i32 m0, s90, s55
	s_nop 0
	global_load_lds_dwordx4 v162, s[92:93] sc1
.Lfa_ls2:
	s_waitcnt lgkmcnt(3)
	v_mfma_f32_32x32x16_bf16 v[80:95], v[172:175], v[116:119], v[80:95]
	ds_read_b128 v[172:175], v144 offset:288
	s_waitcnt lgkmcnt(3)
	v_mfma_f32_32x32x16_bf16 v[80:95], v[176:179], v[120:123], v[80:95]
	ds_read_b128 v[176:179], v144 offset:320
	s_waitcnt lgkmcnt(3)
	v_mfma_f32_32x32x16_bf16 v[80:95], v[180:183], v[124:127], v[80:95]
	ds_read_b128 v[180:183], v144 offset:352
	s_cmp_lg_u32 s96, 0
	s_cbranch_scc0 .Lfa_ls3
	s_add_i32 m0, s90, s82
	s_nop 0
	global_load_lds_dwordx4 v164, s[92:93] sc1
.Lfa_ls3:
	s_waitcnt lgkmcnt(3)
	v_mfma_f32_32x32x16_bf16 v[80:95], v[168:171], v[128:131], v[80:95]
	ds_read_b128 v[168:171], v144 offset:12800
	s_waitcnt lgkmcnt(3)
	v_mfma_f32_32x32x16_bf16 v[80:95], v[172:175], v[132:135], v[80:95]
	ds_read_b128 v[172:175], v144 offset:12832
	s_waitcnt lgkmcnt(3)
	v_mfma_f32_32x32x16_bf16 v[80:95], v[176:179], v[136:139], v[80:95]
	ds_read_b128 v[176:179], v144 offset:12864
	s_cmp_lg_u32 s97, 0
	s_cbranch_scc0 .Lfa_ls4
	s_add_i32 m0, s90, 0x6000
	s_nop 0
	global_load_lds_dwordx4 v166, s[92:93] sc1
.Lfa_ls4:
	s_waitcnt lgkmcnt(3)
	v_mfma_f32_32x32x16_bf16 v[80:95], v[180:183], v[140:143], v[80:95]
	ds_read_b128 v[180:183], v144 offset:12896
	s_waitcnt lgkmcnt(3)
	v_mfma_f32_32x32x16_bf16 v[64:79], v[168:171], v[96:99], v[64:79]
	ds_read_b128 v[168:171], v144 offset:12928
	s_waitcnt lgkmcnt(3)
	v_mfma_f32_32x32x16_bf16 v[64:79], v[172:175], v[100:103], v[64:79]
	ds_read_b128 v[172:175], v144 offset:12960
	s_cmp_lg_u32 s96, 0
	s_cbranch_scc0 .Lfa_ls5
	s_add_i32 m0, s91, s51
	s_nop 0
	global_load_lds_dwordx4 v154, s[94:95] sc1
.Lfa_ls5:
	s_waitcnt lgkmcnt(3)
	v_mfma_f32_32x32x16_bf16 v[64:79], v[176:179], v[104:107], v[64:79]
	ds_read_b128 v[176:179], v144 offset:12992
	s_waitcnt lgkmcnt(3)
	v_mfma_f32_32x32x16_bf16 v[64:79], v[180:183], v[108:111], v[64:79]
	ds_read_b128 v[180:183], v144 offset:13024
	s_waitcnt lgkmcnt(3)
	v_mfma_f32_32x32x16_bf16 v[64:79], v[168:171], v[112:115], v[64:79]
	ds_read_b128 v[168:171], v144 offset:13056
	s_cmp_lg_u32 s96, 0
	s_cbranch_scc0 .Lfa_ls6
	s_add_i32 m0, s91, s55
	s_nop 0
	global_load_lds_dwordx4 v156, s[94:95] sc1
.Lfa_ls6:
	v_max_f32_e32 v243, v81, v81
	v_max_f32_e32 v210, v80, v80
	s_waitcnt lgkmcnt(3)
	v_mfma_f32_32x32x16_bf16 v[64:79], v[172:175], v[116:119], v[64:79]
	ds_read_b128 v[172:175], v144 offset:13088
	v_max_f32_e32 v243, v210, v243
	v_max3_f32 v243, v243, v82, v83
	s_waitcnt lgkmcnt(3)
	v_mfma_f32_32x32x16_bf16 v[64:79], v[176:179], v[120:123], v[64:79]
	ds_read_b128 v[176:179], v144 offset:13120
	v_max3_f32 v243, v243, v84, v85
	v_max3_f32 v243, v243, v86, v87
	s_waitcnt lgkmcnt(3)
	v_mfma_f32_32x32x16_bf16 v[64:79], v[180:183], v[124:127], v[64:79]
	ds_read_b128 v[180:183], v144 offset:13152
	s_cmp_lg_u32 s99, 0
	s_cbranch_scc0 .Lfa_ls7
	s_add_i32 m0, s91, s82
	s_nop 0
	global_load_lds_dwordx4 v158, s[94:95] sc1

.Lfa_noqk:
	s_cmp_lg_u32 s96, 0
	s_cbranch_scc0 .Lfa_ls8
	s_add_i32 m0, s90, s51
	s_nop 0
	global_load_lds_dwordx4 v160, s[92:93] sc1
.Lfa_ls8:
	s_cmp_lg_u32 s96, 0
	s_cbranch_scc0 .Lfa_ls9
	s_add_i32 m0, s90, s55
	s_nop 0
	global_load_lds_dwordx4 v162, s[92:93] sc1
.Lfa_ls9:
	s_cmp_lg_u32 s96, 0
	s_cbranch_scc0 .Lfa_ls10
	s_add_i32 m0, s90, s82
	s_nop 0
	global_load_lds_dwordx4 v164, s[92:93] sc1
.Lfa_ls10:
	s_cmp_lg_u32 s97, 0
	s_cbranch_scc0 .Lfa_ls11
	s_add_i32 m0, s90, 0x6000
	s_nop 0
	global_load_lds_dwordx4 v166, s[92:93] sc1
.Lfa_ls11:
	s_cmp_lg_u32 s96, 0
	s_cbranch_scc0 .Lfa_ls12
	s_add_i32 m0, s91, s51
	s_nop 0
	global_load_lds_dwordx4 v154, s[94:95] sc1
.Lfa_ls12:
	s_cmp_lg_u32 s96, 0
	s_cbranch_scc0 .Lfa_ls13
	s_add_i32 m0, s91, s55
	s_nop 0
	global_load_lds_dwordx4 v156, s[94:95] sc1
.Lfa_ls13:
	s_cmp_lg_u32 s99, 0
	s_cbranch_scc0 .Lfa_ls14
	s_add_i32 m0, s91, s82
	s_nop 0
	global_load_lds_dwordx4 v158, s[94:95] sc1

.LBB0_1342:
	s_add_i32 s12, s88, 0
	s_add_i32 m0, s12, 0x6400
	s_nop 0
	global_load_lds_dwordx4 v144, s[52:53] sc1
	v_cndmask_b32_e64 v0, 0, 1, s[14:15]
	v_cmp_ne_u32_e64 s[12:13], 1, v0
	s_andn2_b64 vcc, exec, s[14:15]
	s_cbranch_vccnz .LBB0_1243
.LBB0_1343:
	s_lshl_b32 s14, s89, 10
	s_add_i32 s14, s14, 0
	s_add_i32 m0, s14, 0x6400
	s_nop 0
	global_load_lds_dwordx4 v128, s[52:53] sc1
	v_cndmask_b32_e64 v0, 0, 1, s[16:17]
	v_cmp_ne_u32_e64 s[14:15], 1, v0
	s_andn2_b64 vcc, exec, s[16:17]
	s_cbranch_vccnz .LBB0_1244
.LBB0_1344:
	s_mov_b32 m0, s78
	s_nop 0
	global_load_lds_dwordx4 v130, s[52:53] sc1
	v_cndmask_b32_e64 v0, 0, 1, s[18:19]
	v_cmp_ne_u32_e64 s[16:17], 1, v0
	s_andn2_b64 vcc, exec, s[18:19]
	s_cbranch_vccnz .LBB0_1245
.LBB0_1345:
	v_mov_b32_e32 v133, v145
	v_lshl_add_u64 v[0:1], s[6:7], 0, v[132:133]
	s_add_i32 s18, s88, 0
	v_lshl_add_u64 v[0:1], v[0:1], 0, s[26:27]
	s_add_i32 m0, s18, 0x11000
	s_nop 0
	global_load_lds_dwordx4 v[0:1], off sc1
	v_cndmask_b32_e64 v0, 0, 1, s[20:21]
	v_cmp_ne_u32_e64 s[18:19], 1, v0
	s_andn2_b64 vcc, exec, s[20:21]
	s_cbranch_vccnz .LBB0_1246
.LBB0_1346:
	v_mov_b32_e32 v135, v145
	s_lshl_b32 s20, s89, 10
	v_lshl_add_u64 v[0:1], s[6:7], 0, v[134:135]
	s_add_i32 s20, s20, 0
	v_lshl_add_u64 v[0:1], v[0:1], 0, s[26:27]
	s_add_i32 m0, s20, 0x11000
	s_nop 0
	global_load_lds_dwordx4 v[0:1], off sc1
	v_cndmask_b32_e64 v0, 0, 1, s[48:49]
	v_cmp_ne_u32_e64 s[20:21], 1, v0
	s_andn2_b64 vcc, exec, s[48:49]
	s_cbranch_vccz .LBB0_1247
	s_branch .LBB0_1248
.LBB0_1347:
	v_lshl_add_u64 v[66:67], s[54:55], 0, v[144:145]
	s_add_i32 m0, s88, 0
	s_nop 0
	global_load_lds_dwordx4 v[66:67], off sc1
	v_mov_b32_e32 v129, v145
	s_and_b64 vcc, exec, s[12:13]
	s_lshl_b32 s24, s89, 10
	s_cbranch_vccnz .LBB0_1252
.LBB0_1348:
	v_lshl_add_u64 v[66:67], s[54:55], 0, v[128:129]
	s_add_i32 m0, s24, 0
	s_nop 0
	global_load_lds_dwordx4 v[66:67], off sc1
	s_and_b64 vcc, exec, s[14:15]
	v_mov_b32_e32 v131, v145
	s_cbranch_vccnz .LBB0_1253
.LBB0_1349:
	v_lshl_add_u64 v[66:67], s[54:55], 0, v[130:131]
	s_add_i32 m0, 0, 0x4000
	s_nop 0
	global_load_lds_dwordx4 v[66:67], off sc1
	v_mov_b32_e32 v133, v145
	s_and_b64 vcc, exec, s[16:17]
	v_lshl_add_u64 v[132:133], s[6:7], 0, v[132:133]
	s_cbranch_vccnz .LBB0_1254
.LBB0_1350:
	s_add_i32 s8, s88, 0
	v_lshl_add_u64 v[66:67], v[132:133], 0, s[28:29]
	s_add_i32 m0, s8, 0x15800
	s_nop 0
	global_load_lds_dwordx4 v[66:67], off sc1
	v_mov_b32_e32 v135, v145
	s_and_b64 vcc, exec, s[18:19]
	v_lshl_add_u64 v[134:135], s[6:7], 0, v[134:135]
	s_cbranch_vccz .LBB0_1255
	s_branch .LBB0_1256
.LBB0_1351:
	s_add_i32 s10, s88, 0
	v_lshl_add_u64 v[166:167], s[50:51], 0, v[144:145]
	s_add_i32 m0, s10, 0x6400
	s_nop 0
	global_load_lds_dwordx4 v[166:167], off sc1
	s_and_b64 vcc, exec, s[12:13]
	s_cbranch_vccnz .LBB0_1266
.LBB0_1352:
	s_add_i32 s10, s24, 0
	v_lshl_add_u64 v[128:129], s[50:51], 0, v[128:129]
	s_add_i32 m0, s10, 0x6400
	s_nop 0
	global_load_lds_dwordx4 v[128:129], off sc1
	s_and_b64 vcc, exec, s[14:15]
	s_cbranch_vccnz .LBB0_1267
.LBB0_1353:
	v_lshl_add_u64 v[128:129], s[50:51], 0, v[130:131]
	s_mov_b32 m0, s78
	s_nop 0
	global_load_lds_dwordx4 v[128:129], off sc1
	s_and_b64 vcc, exec, s[16:17]
	s_cbranch_vccnz .LBB0_1268
.LBB0_1354:
	s_add_i32 s10, s88, 0
	v_lshl_add_u64 v[128:129], v[132:133], 0, s[30:31]
	s_add_i32 m0, s10, 0xc800
	s_nop 0
	global_load_lds_dwordx4 v[128:129], off sc1
	s_and_b64 vcc, exec, s[18:19]
	s_cbranch_vccnz .LBB0_1269
.LBB0_1355:
	s_add_i32 s10, s24, 0
	v_lshl_add_u64 v[128:129], v[134:135], 0, s[30:31]
	s_add_i32 m0, s10, 0xc800
	s_nop 0
	global_load_lds_dwordx4 v[128:129], off sc1
	s_and_b64 vcc, exec, s[20:21]
	s_cbranch_vccnz .LBB0_1270
.LBB0_1356:
	s_add_i32 s10, s54, 0
	v_lshl_add_u64 v[128:129], v[136:137], 0, s[30:31]
	s_add_i32 m0, s10, 0xc800
	s_nop 0
	global_load_lds_dwordx4 v[128:129], off sc1
	s_and_b64 vcc, exec, s[6:7]
	s_cbranch_vccz .LBB0_1271
	s_branch .LBB0_1272
.LBB0_1357:
	s_add_i32 s6, s51, 0
	s_add_i32 m0, s6, 0x6400
	s_nop 0
	global_load_lds_dwordx4 v160, s[48:49] sc1
	v_cndmask_b32_e64 v0, 0, 1, s[8:9]
	v_cmp_ne_u32_e64 s[6:7], 1, v0
	s_andn2_b64 vcc, exec, s[8:9]
	s_cbranch_vccnz .LBB0_1302
.LBB0_1358:
	s_lshl_b32 s8, s55, 10
	s_add_i32 s8, s8, 0
	s_add_i32 m0, s8, 0x6400
	s_nop 0
	global_load_lds_dwordx4 v162, s[48:49] sc1
	v_cndmask_b32_e64 v0, 0, 1, s[10:11]
	v_cmp_ne_u32_e64 s[8:9], 1, v0
	s_andn2_b64 vcc, exec, s[10:11]
	s_cbranch_vccnz .LBB0_1303
.LBB0_1359:
	s_lshl_b32 s10, s82, 10
	s_add_i32 s10, s10, 0
	s_add_i32 m0, s10, 0x6400
	s_nop 0
	global_load_lds_dwordx4 v164, s[48:49] sc1
	v_cndmask_b32_e64 v0, 0, 1, s[12:13]
	v_cmp_ne_u32_e64 s[10:11], 1, v0
	s_andn2_b64 vcc, exec, s[12:13]
	s_cbranch_vccnz .LBB0_1304
.LBB0_1360:
	s_mov_b32 m0, s83
	s_nop 0
	global_load_lds_dwordx4 v166, s[48:49] sc1
	v_cndmask_b32_e64 v0, 0, 1, s[14:15]
	v_cmp_ne_u32_e64 s[12:13], 1, v0
	s_andn2_b64 vcc, exec, s[14:15]
	s_cbranch_vccnz .LBB0_1305
.LBB0_1361:
	s_add_i32 s14, s51, 0
	v_lshl_add_u64 v[0:1], s[20:21], 0, v[144:145]
	s_add_i32 m0, s14, 0x11000
	v_lshl_add_u64 v[0:1], v[0:1], 0, s[26:27]
	global_load_lds_dwordx4 v[0:1], off sc1
	v_cndmask_b32_e64 v0, 0, 1, s[16:17]
	v_cmp_ne_u32_e64 s[14:15], 1, v0
	s_andn2_b64 vcc, exec, s[16:17]
	s_cbranch_vccnz .LBB0_1306
.LBB0_1362:
	s_lshl_b32 s16, s55, 10
	v_mov_b32_e32 v157, v145
	s_add_i32 s16, s16, 0
	v_lshl_add_u64 v[0:1], s[20:21], 0, v[156:157]
	s_add_i32 m0, s16, 0x11000
	v_lshl_add_u64 v[0:1], v[0:1], 0, s[26:27]
	global_load_lds_dwordx4 v[0:1], off sc1
	v_cndmask_b32_e64 v0, 0, 1, s[38:39]
	v_cmp_ne_u32_e64 s[16:17], 1, v0
	s_andn2_b64 vcc, exec, s[38:39]
	s_cbranch_vccz .LBB0_1307
	s_branch .LBB0_1308
